# chunk MLP: row-norm (VSS) loads issued together with the V/U tile loads, one counted wait instead of two serial round trips; no store drain before the task-top barrier
# baseline (speedup 1.0000x reference)
.LBB0_349:
	v_or_b32_e32 v0, s50, v20
	v_mov_b64_e32 v[54:55], s[46:47]
	s_mul_i32 s33, s51, 0x3400
	v_mad_u64_u32 v[0:1], s[4:5], v0, s54, v[54:55]
	v_add_u32_e32 v1, s33, v1
	s_lshl_b32 s16, s52, 8
	v_or_b32_e32 v2, s50, v28
	v_lshl_add_u64 v[0:1], v[0:1], 0, s[16:17]
	v_mad_u64_u32 v[2:3], s[4:5], v2, s54, v[54:55]
	v_lshl_add_u64 v[0:1], v[0:1], 0, v[22:23]
	v_add_u32_e32 v3, s33, v3
	v_add_co_u32_e32 v0, vcc, s27, v0
	v_lshl_add_u64 v[2:3], v[2:3], 0, s[16:17]
	s_nop 0
	v_addc_co_u32_e32 v1, vcc, 0, v1, vcc
	v_lshl_add_u64 v[2:3], v[2:3], 0, v[22:23]
	v_add_co_u32_e32 v2, vcc, s27, v2
	v_mov_b32_e32 v51, v23
	s_nop 0
	v_addc_co_u32_e32 v3, vcc, 0, v3, vcc
	flat_load_dwordx4 v[4:7], v[0:1] offset:3072
	flat_load_dwordx4 v[8:11], v[2:3] offset:3072
	v_lshl_add_u64 v[2:3], s[50:51], 0, v[32:33]
	v_mad_u64_u32 v[16:17], s[4:5], v2, s54, v[54:55]
	v_mov_b32_e32 v2, v17
	v_mad_u64_u32 v[2:3], s[4:5], v3, s54, v[2:3]
	v_or_b32_e32 v0, s50, v30
	v_mov_b32_e32 v17, v2
	v_mad_u64_u32 v[0:1], s[4:5], v0, s54, v[54:55]
	v_lshl_add_u64 v[2:3], v[16:17], 0, s[16:17]
	v_lshl_add_u64 v[16:17], s[50:51], 0, v[26:27]
	v_add_u32_e32 v1, s33, v1
	v_mad_u64_u32 v[18:19], s[4:5], v16, s54, v[54:55]
	v_lshl_add_u64 v[0:1], v[0:1], 0, s[16:17]
	v_mov_b32_e32 v16, v19
	v_lshl_add_u64 v[0:1], v[0:1], 0, v[22:23]
	v_mad_u64_u32 v[16:17], s[4:5], v17, s54, v[16:17]
	v_add_co_u32_e32 v0, vcc, s27, v0
	v_mov_b32_e32 v19, v16
	s_nop 0
	v_addc_co_u32_e32 v1, vcc, 0, v1, vcc
	v_lshl_add_u64 v[2:3], v[2:3], 0, v[22:23]
	v_lshl_add_u64 v[16:17], v[18:19], 0, s[16:17]
	v_add_co_u32_e32 v2, vcc, s27, v2
	v_mov_b32_e32 v53, v23
	v_lshl_add_u64 v[16:17], v[16:17], 0, v[50:51]
	v_addc_co_u32_e32 v3, vcc, 0, v3, vcc
	v_lshl_add_u64 v[16:17], v[16:17], 0, v[52:53]
	v_add_co_u32_e32 v62, vcc, s27, v16
	v_lshl_add_u64 v[60:61], v[16:17], 0, s[22:23]
	s_nop 0
	v_addc_co_u32_e32 v63, vcc, 0, v17, vcc
	v_lshl_add_u64 v[64:65], v[16:17], 0, s[24:25]
	v_add_co_u32_e32 v16, vcc, s57, v16
	s_lshl_b32 s4, s52, 9
	s_nop 0
	v_addc_co_u32_e32 v17, vcc, 0, v17, vcc
	s_mov_b32 s5, s17
	flat_load_dwordx4 v[112:115], v[0:1] offset:3072
	s_nop 0
	flat_load_dwordx4 v[0:3], v[2:3] offset:3072
	s_nop 0
	flat_load_dwordx2 v[72:73], v[62:63] offset:1024
	flat_load_dwordx2 v[70:71], v[60:61] offset:32
	flat_load_dwordx2 v[68:69], v[60:61] offset:64
	flat_load_dwordx2 v[66:67], v[60:61] offset:96
	flat_load_dwordx2 v[58:59], v[16:17] offset:1024
	flat_load_dwordx2 v[56:57], v[64:65] offset:32
	flat_load_dwordx2 v[18:19], v[64:65] offset:64
	s_nop 0
	flat_load_dwordx2 v[16:17], v[64:65] offset:96
	v_lshl_add_u64 v[64:65], v[14:15], 0, s[4:5]
	s_and_saveexec_b64 s[86:87], s[6:7]
	s_cbranch_execz .Lmlp_rs_done
	s_waitcnt vmcnt(12)
	v_pk_add_f32 v[208:209], v[208:209], v[212:213]
	v_pk_add_f32 v[210:211], v[210:211], v[214:215]
	v_pk_add_f32 v[208:209], v[208:209], v[216:217]
	v_pk_add_f32 v[210:211], v[210:211], v[218:219]
	v_pk_add_f32 v[208:209], v[208:209], v[220:221]
	v_pk_add_f32 v[210:211], v[210:211], v[222:223]
	v_add_f32_e32 v208, v208, v209
	v_add_f32_e32 v208, v210, v208
	v_add_f32_e32 v208, v211, v208
	v_fmamk_f32 v208, v208, 0x3a800000, v105
	v_mul_f32_e32 v209, 0x4b800000, v208
	v_cmp_gt_f32_e64 s[84:85], s56, v208
	s_nop 1
	v_cndmask_b32_e64 v208, v208, v209, s[84:85]
	v_rsq_f32_e32 v208, v208
	s_nop 0
	v_mul_f32_e32 v209, 0x45800000, v208
	v_cndmask_b32_e64 v208, v208, v209, s[84:85]
	ds_write_b32 v21, v208
.Lmlp_rs_done:
	s_or_b64 exec, exec, s[86:87]
	s_waitcnt lgkmcnt(0)
	s_barrier
	flat_load_dwordx4 v[116:119], v[64:65]
	flat_load_dwordx4 v[120:123], v[64:65] offset:16
	ds_read_b32 v43, v25
	ds_read_b32 v47, v94
	ds_read_b32 v49, v97
	ds_read_b32 v111, v100
	s_add_i32 s60, s60, s38
	s_add_i32 s59, s59, s39
	s_cmpk_lt_i32 s60, 0x1000
	s_waitcnt vmcnt(0)
	v_lshlrev_b32_e32 v45, 16, v4
	v_and_b32_e32 v4, 0xffff0000, v4
	s_waitcnt lgkmcnt(0)
	v_mul_f32_e32 v4, v43, v4
	v_mul_f32_e32 v45, v43, v45
	v_lshlrev_b32_e32 v74, 16, v5
	v_and_b32_e32 v5, 0xffff0000, v5
	v_mul_f32_e32 v74, v43, v74
	v_mul_f32_e32 v5, v43, v5
	v_lshlrev_b32_e32 v75, 16, v6
	v_and_b32_e32 v6, 0xffff0000, v6
	v_mul_f32_e32 v75, v43, v75
	v_mul_f32_e32 v6, v43, v6
	v_lshlrev_b32_e32 v176, 16, v70
	v_and_b32_e32 v177, 0xffff0000, v70
	v_lshlrev_b32_e32 v178, 16, v71
	v_and_b32_e32 v179, 0xffff0000, v71
	v_lshlrev_b32_e32 v182, 16, v69
	v_and_b32_e32 v183, 0xffff0000, v69
	v_lshlrev_b32_e32 v180, 16, v68
	v_mul_f32_e32 v4, v4, v117
	v_mul_f32_e32 v45, v45, v116
	v_cvt_pk_bf16_f32 v4, v45, v4
	v_mul_f32_e32 v74, v74, v118
	v_mul_f32_e32 v5, v5, v119
	v_lshlrev_b32_e32 v116, 16, v7
	v_and_b32_e32 v7, 0xffff0000, v7
	ds_write_b16 v29, v4 offset:34816
	ds_write_b16_d16_hi v31, v4 offset:35088
	v_cvt_pk_bf16_f32 v4, v74, v5
	v_mul_f32_e32 v75, v75, v120
	v_mul_f32_e32 v6, v6, v121
	v_mul_f32_e32 v116, v43, v116
	v_mul_f32_e32 v7, v43, v7
	ds_write_b16 v29, v4 offset:35360
	ds_write_b16_d16_hi v31, v4 offset:35632
	v_cvt_pk_bf16_f32 v4, v75, v6
	v_mul_f32_e32 v116, v116, v122
	v_mul_f32_e32 v7, v7, v123
	ds_write_b16 v29, v4 offset:35904
	ds_write_b16_d16_hi v31, v4 offset:36176
	v_cvt_pk_bf16_f32 v4, v116, v7
	ds_write_b16 v29, v4 offset:36448
	ds_write_b16_d16_hi v31, v4 offset:36720
	flat_load_dwordx4 v[4:7], v[64:65]
	flat_load_dwordx4 v[116:119], v[64:65] offset:16
	v_lshlrev_b32_e32 v43, 16, v8
	v_and_b32_e32 v8, 0xffff0000, v8
	v_lshlrev_b32_e32 v45, 16, v9
	v_and_b32_e32 v9, 0xffff0000, v9
	v_mul_f32_e32 v43, v47, v43
	v_lshlrev_b32_e32 v74, 16, v10
	v_and_b32_e32 v10, 0xffff0000, v10
	v_lshlrev_b32_e32 v75, 16, v11
	v_and_b32_e32 v11, 0xffff0000, v11
	v_mul_f32_e32 v8, v47, v8
	v_mul_f32_e32 v45, v47, v45
	v_mul_f32_e32 v9, v47, v9
	v_mul_f32_e32 v74, v47, v74
	v_mul_f32_e32 v10, v47, v10
	v_mul_f32_e32 v75, v47, v75
	v_mul_f32_e32 v11, v47, v11
	v_lshlrev_b32_e32 v47, 16, v113
	v_mul_f32_e32 v47, v49, v47
	v_lshlrev_b32_e32 v120, 16, v2
	v_and_b32_e32 v121, 0xffff0000, v2
	v_lshlrev_b32_e32 v122, 16, v3
	v_and_b32_e32 v123, 0xffff0000, v3
	v_mul_f32_e32 v124, v111, v120
	v_mul_f32_e32 v125, v111, v121
	v_mul_f32_e32 v122, v111, v122
	v_and_b32_e32 v181, 0xffff0000, v68
	v_lshlrev_b32_e32 v184, 16, v66
	v_and_b32_e32 v185, 0xffff0000, v66
	v_lshlrev_b32_e32 v186, 16, v67
	v_and_b32_e32 v187, 0xffff0000, v67
	v_pk_mul_f32 v[66:67], v[176:177], v[176:177]
	v_pk_mul_f32 v[68:69], v[178:179], v[178:179]
	v_pk_mul_f32 v[70:71], v[180:181], v[180:181]
	s_waitcnt vmcnt(0) lgkmcnt(0)
	v_mul_f32_e32 v4, v43, v4
	v_mul_f32_e32 v5, v8, v5
	v_mul_f32_e32 v6, v45, v6
	v_mul_f32_e32 v7, v9, v7
	v_cvt_pk_bf16_f32 v4, v4, v5
	v_mul_f32_e32 v8, v74, v116
	v_mul_f32_e32 v9, v10, v117
	v_mul_f32_e32 v10, v75, v118
	v_mul_f32_e32 v11, v11, v119
	v_cvt_pk_bf16_f32 v5, v6, v7
	v_cvt_pk_bf16_f32 v6, v8, v9
	v_cvt_pk_bf16_f32 v7, v10, v11
	ds_write_b16 v95, v4 offset:34816
	ds_write_b16_d16_hi v96, v4 offset:35088
	ds_write_b16 v95, v5 offset:35360
	ds_write_b16_d16_hi v96, v5 offset:35632
	ds_write_b16 v95, v6 offset:35904
	ds_write_b16_d16_hi v96, v6 offset:36176
	ds_write_b16 v95, v7 offset:36448
	ds_write_b16_d16_hi v96, v7 offset:36720
	flat_load_dwordx4 v[4:7], v[64:65]
	flat_load_dwordx4 v[8:11], v[64:65] offset:16
	v_lshlrev_b32_e32 v43, 16, v112
	v_and_b32_e32 v45, 0xffff0000, v112
	v_and_b32_e32 v74, 0xffff0000, v113
	v_mul_f32_e32 v43, v49, v43
	v_lshlrev_b32_e32 v75, 16, v114
	v_and_b32_e32 v112, 0xffff0000, v114
	v_lshlrev_b32_e32 v113, 16, v115
	v_and_b32_e32 v114, 0xffff0000, v115
	v_mul_f32_e32 v45, v49, v45
	v_mul_f32_e32 v74, v49, v74
	v_mul_f32_e32 v75, v49, v75
	v_mul_f32_e32 v112, v49, v112
	v_mul_f32_e32 v113, v49, v113
	v_mul_f32_e32 v49, v49, v114
	v_pk_mul_f32 v[114:115], v[182:183], v[182:183]
	v_pk_mul_f32 v[118:119], v[186:187], v[186:187]
	v_pk_mul_f32 v[116:117], v[184:185], v[184:185]
	s_waitcnt vmcnt(0) lgkmcnt(0)
	v_mul_f32_e32 v4, v43, v4
	v_mul_f32_e32 v5, v45, v5
	v_mul_f32_e32 v6, v47, v6
	v_mul_f32_e32 v7, v74, v7
	v_cvt_pk_bf16_f32 v4, v4, v5
	v_mul_f32_e32 v8, v75, v8
	v_mul_f32_e32 v9, v112, v9
	v_mul_f32_e32 v10, v113, v10
	v_mul_f32_e32 v11, v49, v11
	v_cvt_pk_bf16_f32 v5, v6, v7
	v_cvt_pk_bf16_f32 v6, v8, v9
	v_cvt_pk_bf16_f32 v7, v10, v11
	ds_write_b16 v98, v4 offset:34816
	ds_write_b16_d16_hi v99, v4 offset:35088
	ds_write_b16 v98, v5 offset:35360
	ds_write_b16_d16_hi v99, v5 offset:35632
	ds_write_b16 v98, v6 offset:35904
	ds_write_b16_d16_hi v99, v6 offset:36176
	ds_write_b16 v98, v7 offset:36448
	ds_write_b16_d16_hi v99, v7 offset:36720
	flat_load_dwordx4 v[8:11], v[64:65]
	flat_load_dwordx4 v[4:7], v[64:65] offset:16
	v_or_b32_e32 v43, s52, v92
	v_mov_b32_e32 v75, v23
	v_lshlrev_b32_e32 v74, 2, v43
	v_lshl_add_u64 v[112:113], s[36:37], 0, v[74:75]
	v_lshlrev_b32_e32 v74, 16, v72
	v_and_b32_e32 v75, 0xffff0000, v72
	v_lshlrev_b32_e32 v72, 16, v73
	v_and_b32_e32 v73, 0xffff0000, v73
	v_mov_b64_e32 v[64:65], s[28:29]
	v_pk_mul_f32 v[2:3], v[72:73], v[72:73]
	v_lshlrev_b32_e32 v43, 16, v0
	v_pk_fma_f32 v[2:3], v[2:3], s[26:27], v[64:65] op_sel_hi:[1,0,0] neg_lo:[1,0,0] neg_hi:[1,0,0]
	v_and_b32_e32 v45, 0xffff0000, v0
	v_mul_f32_e32 v43, v111, v43
	v_pk_mul_f32 v[2:3], v[2:3], v[72:73]
	v_lshlrev_b32_e32 v47, 16, v1
	v_and_b32_e32 v49, 0xffff0000, v1
	v_mul_f32_e32 v45, v111, v45
	v_exp_f32_e32 v120, v2
	v_mul_f32_e32 v47, v111, v47
	v_mul_f32_e32 v49, v111, v49
	v_mul_f32_e32 v111, v111, v123
	v_exp_f32_e32 v121, v3
	v_pk_mul_f32 v[0:1], v[74:75], v[74:75]
	v_pk_fma_f32 v[66:67], v[66:67], s[26:27], v[64:65] op_sel_hi:[1,0,0] neg_lo:[1,0,0] neg_hi:[1,0,0]
	v_pk_fma_f32 v[0:1], v[0:1], s[26:27], v[64:65] op_sel_hi:[1,0,0] neg_lo:[1,0,0] neg_hi:[1,0,0]
	v_pk_fma_f32 v[68:69], v[68:69], s[26:27], v[64:65] op_sel_hi:[1,0,0] neg_lo:[1,0,0] neg_hi:[1,0,0]
	v_pk_fma_f32 v[114:115], v[114:115], s[26:27], v[64:65] op_sel_hi:[1,0,0] neg_lo:[1,0,0] neg_hi:[1,0,0]
	v_pk_mul_f32 v[0:1], v[0:1], v[74:75]
	v_pk_mul_f32 v[66:67], v[66:67], v[176:177]
	v_pk_mul_f32 v[68:69], v[68:69], v[178:179]
	v_pk_mul_f32 v[114:115], v[114:115], v[182:183]
	v_exp_f32_e32 v0, v0
	v_exp_f32_e32 v1, v1
	v_exp_f32_e32 v66, v66
	v_exp_f32_e32 v67, v67
	v_exp_f32_e32 v68, v68
	v_exp_f32_e32 v69, v69
	v_exp_f32_e32 v123, v115
	v_pk_fma_f32 v[118:119], v[118:119], s[26:27], v[64:65] op_sel_hi:[1,0,0] neg_lo:[1,0,0] neg_hi:[1,0,0]
	v_pk_add_f32 v[136:137], v[0:1], 1.0 op_sel_hi:[1,0]
	v_pk_mul_f32 v[118:119], v[118:119], v[186:187]
	v_pk_add_f32 v[140:141], v[120:121], 1.0 op_sel_hi:[1,0]
	v_exp_f32_e32 v128, v118
	v_exp_f32_e32 v129, v119
	v_pk_add_f32 v[144:145], v[66:67], 1.0 op_sel_hi:[1,0]
	v_pk_add_f32 v[148:149], v[68:69], 1.0 op_sel_hi:[1,0]
	v_pk_fma_f32 v[116:117], v[116:117], s[26:27], v[64:65] op_sel_hi:[1,0,0] neg_lo:[1,0,0] neg_hi:[1,0,0]
	v_pk_add_f32 v[172:173], v[128:129], 1.0 op_sel_hi:[1,0]
	v_pk_mul_f32 v[116:117], v[116:117], v[184:185]
	v_rcp_f32_e32 v174, v136
	v_rcp_f32_e32 v175, v137
	v_rcp_f32_e32 v188, v140
	v_rcp_f32_e32 v189, v141
	v_rcp_f32_e32 v190, v144
	v_rcp_f32_e32 v191, v145
	v_rcp_f32_e32 v192, v148
	v_rcp_f32_e32 v193, v149
	v_pk_fma_f32 v[70:71], v[70:71], s[26:27], v[64:65] op_sel_hi:[1,0,0] neg_lo:[1,0,0] neg_hi:[1,0,0]
	v_rcp_f32_e32 v202, v172
	v_pk_mul_f32 v[70:71], v[70:71], v[180:181]
	v_rcp_f32_e32 v203, v173
	v_exp_f32_e32 v70, v70
	v_exp_f32_e32 v71, v71
	v_pk_mul_f32 v[74:75], v[174:175], v[74:75]
	v_pk_mul_f32 v[204:205], v[188:189], v[72:73]
	v_pk_mul_f32 v[206:207], v[190:191], v[176:177]
	v_pk_add_f32 v[70:71], v[70:71], 1.0 op_sel_hi:[1,0]
	v_pk_mul_f32 v[192:193], v[192:193], v[178:179]
	v_rcp_f32_e32 v194, v70
	v_rcp_f32_e32 v195, v71
	v_pk_mul_f32 v[202:203], v[202:203], v[186:187]
	v_pk_mul_f32 v[194:195], v[194:195], v[180:181]
	s_waitcnt vmcnt(0) lgkmcnt(0)
	v_mul_f32_e32 v2, v43, v8
	v_mul_f32_e32 v3, v45, v9
	v_mul_f32_e32 v4, v124, v4
	v_mul_f32_e32 v5, v125, v5
	v_cvt_pk_bf16_f32 v2, v2, v3
	v_mul_f32_e32 v8, v47, v10
	v_mul_f32_e32 v9, v49, v11
	v_mul_f32_e32 v6, v122, v6
	v_mul_f32_e32 v7, v111, v7
	v_cvt_pk_bf16_f32 v3, v8, v9
	v_cvt_pk_bf16_f32 v4, v4, v5
	v_cvt_pk_bf16_f32 v5, v6, v7
	ds_write_b16 v101, v2 offset:34816
	ds_write_b16_d16_hi v102, v2 offset:35088
	ds_write_b16 v101, v3 offset:35360
	ds_write_b16_d16_hi v102, v3 offset:35632
	ds_write_b16 v101, v4 offset:35904
	ds_write_b16_d16_hi v102, v4 offset:36176
	ds_write_b16 v101, v5 offset:36448
	ds_write_b16_d16_hi v102, v5 offset:36720
	s_waitcnt lgkmcnt(0)
	s_barrier
	flat_load_dword v43, v[112:113]
	v_exp_f32_e32 v122, v114
	ds_read_b128 v[0:3], v76 offset:34816
	ds_read_b128 v[4:7], v110
	ds_read_b128 v[8:11], v77 offset:34816
	ds_read_b128 v[66:69], v78 offset:34816
	ds_read_b128 v[112:115], v110 offset:64
	v_pk_add_f32 v[164:165], v[122:123], 1.0 op_sel_hi:[1,0]
	ds_read_b128 v[120:123], v79 offset:34816
	ds_read_b128 v[128:131], v80 offset:34816
	ds_read_b128 v[136:139], v81 offset:34816
	ds_read_b128 v[140:143], v82 offset:34816
	ds_read_b128 v[144:147], v83 offset:34816
	ds_read_b128 v[148:151], v84 offset:34816
	v_exp_f32_e32 v124, v116
	v_exp_f32_e32 v125, v117
	s_waitcnt lgkmcnt(0)
	v_mfma_f32_16x16x32_bf16 v[116:119], v[0:3], v[4:7], 0
	ds_read_b128 v[152:155], v110 offset:128
	ds_read_b128 v[156:159], v85 offset:34816
	v_rcp_f32_e32 v198, v164
	v_pk_add_f32 v[168:169], v[124:125], 1.0 op_sel_hi:[1,0]
	v_mfma_f32_16x16x32_bf16 v[124:127], v[8:11], v[4:7], 0
	v_rcp_f32_e32 v199, v165
	v_rcp_f32_e32 v200, v168
	v_rcp_f32_e32 v201, v169
	v_mfma_f32_16x16x32_bf16 v[132:135], v[66:69], v[4:7], 0
	v_mul_f32_e64 v198, v198, v182
	v_mul_f32_e64 v199, v199, v183
	v_pk_mul_f32 v[200:201], v[200:201], v[184:185]
	v_mfma_f32_16x16x32_bf16 v[4:7], v[120:123], v[4:7], 0
	v_mfma_f32_16x16x32_bf16 v[116:119], v[128:131], v[112:115], v[116:119]
	v_mfma_f32_16x16x32_bf16 v[124:127], v[136:139], v[112:115], v[124:127]
	v_mfma_f32_16x16x32_bf16 v[132:135], v[140:143], v[112:115], v[132:135]
	v_mfma_f32_16x16x32_bf16 v[4:7], v[144:147], v[112:115], v[4:7]
	ds_read_b128 v[112:115], v86 offset:34816
	ds_read_b128 v[160:163], v110 offset:192
	ds_read_b128 v[164:167], v87 offset:34816
	ds_read_b128 v[168:171], v88 offset:34816
	s_waitcnt lgkmcnt(0)
	v_mfma_f32_16x16x32_bf16 v[116:119], v[148:151], v[152:155], v[116:119]
	ds_read_b128 v[172:175], v89 offset:34816
	ds_read_b128 v[70:73], v90 offset:34816
	v_mfma_f32_16x16x32_bf16 v[124:127], v[156:159], v[152:155], v[124:127]
	v_mfma_f32_16x16x32_bf16 v[132:135], v[112:115], v[152:155], v[132:135]
	v_mfma_f32_16x16x32_bf16 v[4:7], v[164:167], v[152:155], v[4:7]
	ds_read_b128 v[152:155], v91 offset:34816
	ds_read_b128 v[176:179], v110 offset:4352
	ds_read_b128 v[180:183], v110 offset:4416
	ds_read_b128 v[184:187], v110 offset:4480
	ds_read_b128 v[188:191], v110 offset:4544
	v_mfma_f32_16x16x32_bf16 v[116:119], v[168:171], v[160:163], v[116:119]
	s_waitcnt lgkmcnt(0)
	v_mfma_f32_16x16x32_bf16 v[124:127], v[172:175], v[160:163], v[124:127]
	v_mfma_f32_16x16x32_bf16 v[132:135], v[70:73], v[160:163], v[132:135]
	s_waitcnt vmcnt(0)
	s_nop 3
	v_add_f32_e32 v45, v116, v43
	v_mfma_f32_16x16x32_bf16 v[4:7], v[152:155], v[160:163], v[4:7]
	v_add_f32_e32 v47, v117, v43
	v_add_f32_e32 v49, v118, v43
	v_add_f32_e32 v111, v119, v43
	v_add_f32_e32 v116, v124, v43
	v_add_f32_e32 v117, v125, v43
	v_add_f32_e32 v118, v126, v43
	v_add_f32_e32 v119, v127, v43
	v_add_f32_e32 v125, v133, v43
	v_add_f32_e32 v126, v134, v43
	v_add_f32_e32 v4, v4, v43
	v_add_f32_e32 v5, v5, v43
	v_add_f32_e32 v124, v132, v43
	v_add_f32_e32 v127, v135, v43
	v_add_f32_e32 v6, v6, v43
	v_add_f32_e32 v7, v7, v43
	v_mul_f32_e32 v43, v74, v45
	v_mul_f32_e32 v45, v75, v47
	v_mul_f32_e32 v47, v204, v49
	v_mul_f32_e32 v49, v205, v111
	v_mul_f32_e32 v74, v206, v116
	v_mul_f32_e32 v75, v207, v117
	v_mul_f32_e32 v111, v192, v118
	v_mul_f32_e32 v116, v193, v119
	v_mul_f32_e32 v118, v195, v125
	v_mul_f32_e32 v119, v198, v126
	v_mul_f32_e32 v125, v200, v4
	v_mul_f32_e32 v126, v201, v5
	v_cvt_pk_bf16_f32 v4, v43, v45
	v_cvt_pk_bf16_f32 v5, v47, v49
	v_mul_f32_e32 v117, v194, v124
	v_mul_f32_e32 v124, v199, v127
	v_mul_f32_e32 v127, v202, v6
	v_mul_f32_e32 v132, v203, v7
	v_cvt_pk_bf16_f32 v6, v74, v75
	v_cvt_pk_bf16_f32 v7, v111, v116
	v_cvt_pk_bf16_f32 v74, v117, v118
	v_cvt_pk_bf16_f32 v75, v119, v124
	flat_store_dwordx2 v[62:63], v[4:5] offset:1024
	flat_store_dwordx2 v[60:61], v[6:7] offset:32
	flat_store_dwordx2 v[60:61], v[74:75] offset:64
	v_or_b32_e32 v4, s52, v93
	v_lshlrev_b32_e32 v4, 2, v4
	v_mov_b32_e32 v5, v23
	v_cvt_pk_bf16_f32 v116, v125, v126
	v_cvt_pk_bf16_f32 v117, v127, v132
	flat_store_dwordx2 v[60:61], v[116:117] offset:96
	v_lshl_add_u64 v[4:5], s[36:37], 0, v[4:5]
	flat_load_dword v43, v[4:5]
	v_lshl_add_u64 v[6:7], s[50:51], 0, v[34:35]
	v_mfma_f32_16x16x32_bf16 v[2:5], v[0:3], v[176:179], 0
	v_mad_u64_u32 v[54:55], s[4:5], v6, s54, v[54:55]
	v_mov_b32_e32 v6, v55
	v_mfma_f32_16x16x32_bf16 v[60:63], v[66:69], v[176:179], 0
	v_mad_u64_u32 v[0:1], s[4:5], v7, s54, v[6:7]
	v_lshlrev_b32_e32 v74, 16, v58
	v_mfma_f32_16x16x32_bf16 v[66:69], v[120:123], v[176:179], 0
	v_and_b32_e32 v75, 0xffff0000, v58
	v_lshlrev_b32_e32 v116, 16, v59
	v_and_b32_e32 v117, 0xffff0000, v59
	v_mov_b32_e32 v55, v0
	v_mfma_f32_16x16x32_bf16 v[6:9], v[8:11], v[176:179], 0
	v_mul_f32_e64 v58, v74, v74
	v_mul_f32_e64 v59, v75, v75
	v_pk_mul_f32 v[122:123], v[116:117], v[116:117]
	v_lshl_add_u64 v[0:1], v[54:55], 0, s[16:17]
	v_mfma_f32_16x16x32_bf16 v[2:5], v[128:131], v[180:183], v[2:5]
	v_lshlrev_b32_e32 v118, 16, v56
	v_and_b32_e32 v119, 0xffff0000, v56
	v_lshlrev_b32_e32 v120, 16, v57
	v_and_b32_e32 v121, 0xffff0000, v57
	v_mfma_f32_16x16x32_bf16 v[54:57], v[140:143], v[180:183], v[60:63]
	v_fma_f32 v122, -v122, s26, v64
	v_fma_f32 v123, -v123, s26, v64
	v_pk_mul_f32 v[124:125], v[118:119], v[118:119]
	v_pk_mul_f32 v[126:127], v[120:121], v[120:121]
	v_pk_fma_f32 v[62:63], v[58:59], s[26:27], v[64:65] op_sel_hi:[1,0,0] neg_lo:[1,0,0] neg_hi:[1,0,0]
	v_mfma_f32_16x16x32_bf16 v[58:61], v[144:147], v[180:183], v[66:69]
	v_mul_f32_e64 v62, v62, v74
	v_mul_f32_e64 v63, v63, v75
	v_pk_fma_f32 v[124:125], v[124:125], s[26:27], v[64:65] op_sel_hi:[1,0,0] neg_lo:[1,0,0] neg_hi:[1,0,0]
	v_exp_f32_e32 v62, v62
	v_pk_mul_f32 v[68:69], v[122:123], v[116:117]
	v_exp_f32_e32 v63, v63
	v_exp_f32_e32 v68, v68
	v_exp_f32_e32 v69, v69
	v_mfma_f32_16x16x32_bf16 v[6:9], v[136:139], v[180:183], v[6:9]
	v_mul_f32_e64 v122, v124, v118
	v_mul_f32_e64 v123, v125, v119
	v_pk_add_f32 v[62:63], v[62:63], 1.0 op_sel_hi:[1,0]
	v_pk_add_f32 v[68:69], v[68:69], 1.0 op_sel_hi:[1,0]
	v_mfma_f32_16x16x32_bf16 v[2:5], v[148:151], v[184:187], v[2:5]
	v_fma_f32 v66, -v126, s26, v64
	v_fma_f32 v67, -v127, s26, v64
	v_rcp_f32_e32 v62, v62
	v_rcp_f32_e32 v63, v63
	v_mfma_f32_16x16x32_bf16 v[54:57], v[112:115], v[184:187], v[54:57]
	v_exp_f32_e32 v112, v122
	v_exp_f32_e32 v113, v123
	v_rcp_f32_e32 v68, v68
	v_mfma_f32_16x16x32_bf16 v[6:9], v[156:159], v[184:187], v[6:9]
	v_rcp_f32_e32 v69, v69
	v_pk_mul_f32 v[66:67], v[66:67], v[120:121]
	v_pk_add_f32 v[112:113], v[112:113], 1.0 op_sel_hi:[1,0]
	v_mfma_f32_16x16x32_bf16 v[2:5], v[168:171], v[188:191], v[2:5]
	v_exp_f32_e32 v66, v66
	v_exp_f32_e32 v67, v67
	v_lshl_add_u64 v[0:1], v[0:1], 0, v[50:51]
	v_mfma_f32_16x16x32_bf16 v[6:9], v[172:175], v[188:191], v[6:9]
	v_rcp_f32_e32 v112, v112
	v_rcp_f32_e32 v113, v113
	v_pk_mul_f32 v[62:63], v[62:63], v[74:75]
	v_pk_mul_f32 v[68:69], v[68:69], v[116:117]
	v_lshl_add_u64 v[10:11], v[0:1], 0, v[52:53]
	v_lshl_add_u64 v[0:1], v[10:11], 0, s[22:23]
	v_add_co_u32_e32 v10, vcc, s27, v10
	v_mfma_f32_16x16x32_bf16 v[54:57], v[70:73], v[188:191], v[54:57]
	s_nop 0
	v_addc_co_u32_e32 v11, vcc, 0, v11, vcc
	s_waitcnt vmcnt(0) lgkmcnt(0)
	v_add_f32_e32 v2, v2, v43
	v_add_f32_e32 v3, v3, v43
	v_add_f32_e32 v4, v4, v43
	v_add_f32_e32 v5, v5, v43
	v_mul_f32_e32 v2, v62, v2
	v_mul_f32_e32 v3, v63, v3
	v_mul_f32_e32 v4, v68, v4
	v_mul_f32_e32 v5, v69, v5
	v_cvt_pk_bf16_f32 v2, v2, v3
	v_cvt_pk_bf16_f32 v3, v4, v5
	v_pk_add_f32 v[4:5], v[66:67], 1.0 op_sel_hi:[1,0]
	flat_store_dwordx2 v[10:11], v[2:3] offset:1024
	v_rcp_f32_e32 v4, v4
	v_rcp_f32_e32 v5, v5
	v_pk_mul_f32 v[2:3], v[112:113], v[118:119]
	v_add_f32_e32 v6, v6, v43
	v_mul_f32_e32 v2, v2, v6
	v_add_f32_e32 v6, v7, v43
	v_mul_f32_e32 v3, v3, v6
	v_pk_mul_f32 v[4:5], v[4:5], v[120:121]
	v_cvt_pk_bf16_f32 v2, v2, v3
	v_add_f32_e32 v3, v8, v43
	v_mul_f32_e32 v3, v4, v3
	v_add_f32_e32 v4, v9, v43
	v_mul_f32_e32 v45, v5, v4
	v_lshlrev_b32_e32 v4, 16, v18
	v_and_b32_e32 v5, 0xffff0000, v18
	v_pk_mul_f32 v[6:7], v[4:5], v[4:5]
	v_lshlrev_b32_e32 v8, 16, v19
	v_pk_fma_f32 v[6:7], v[6:7], s[26:27], v[64:65] op_sel_hi:[1,0,0] neg_lo:[1,0,0] neg_hi:[1,0,0]
	v_and_b32_e32 v9, 0xffff0000, v19
	v_pk_mul_f32 v[6:7], v[6:7], v[4:5]
	v_pk_mul_f32 v[10:11], v[8:9], v[8:9]
	v_exp_f32_e32 v6, v6
	v_exp_f32_e32 v7, v7
	v_pk_fma_f32 v[10:11], v[10:11], s[26:27], v[64:65] op_sel_hi:[1,0,0] neg_lo:[1,0,0] neg_hi:[1,0,0]
	v_cvt_pk_bf16_f32 v3, v3, v45
	flat_store_dwordx2 v[0:1], v[2:3] offset:32
	v_pk_mul_f32 v[10:11], v[10:11], v[8:9]
	v_pk_add_f32 v[6:7], v[6:7], 1.0 op_sel_hi:[1,0]
	v_exp_f32_e32 v10, v10
	v_exp_f32_e32 v11, v11
	v_rcp_f32_e32 v6, v6
	v_rcp_f32_e32 v7, v7
	v_mfma_f32_16x16x32_bf16 v[58:61], v[164:167], v[184:187], v[58:61]
	v_add_f32_e64 v10, v10, 1.0
	v_add_f32_e64 v11, v11, 1.0
	v_pk_mul_f32 v[2:3], v[6:7], v[4:5]
	v_rcp_f32_e32 v10, v10
	v_rcp_f32_e32 v11, v11
	v_add_f32_e32 v6, v54, v43
	v_mul_f32_e32 v2, v2, v6
	v_add_f32_e32 v6, v55, v43
	v_mul_f32_e32 v3, v3, v6
	v_pk_mul_f32 v[4:5], v[10:11], v[8:9]
	v_cvt_pk_bf16_f32 v2, v2, v3
	v_add_f32_e32 v3, v56, v43
	v_mul_f32_e32 v3, v4, v3
	v_add_f32_e32 v4, v57, v43
	v_mul_f32_e32 v18, v5, v4
	v_lshlrev_b32_e32 v4, 16, v16
	v_and_b32_e32 v5, 0xffff0000, v16
	v_pk_mul_f32 v[6:7], v[4:5], v[4:5]
	v_lshlrev_b32_e32 v8, 16, v17
	v_pk_fma_f32 v[6:7], v[6:7], s[26:27], v[64:65] op_sel_hi:[1,0,0] neg_lo:[1,0,0] neg_hi:[1,0,0]
	v_and_b32_e32 v9, 0xffff0000, v17
	v_pk_mul_f32 v[6:7], v[6:7], v[4:5]
	v_pk_mul_f32 v[10:11], v[8:9], v[8:9]
	v_exp_f32_e32 v6, v6
	v_exp_f32_e32 v7, v7
	v_pk_fma_f32 v[10:11], v[10:11], s[26:27], v[64:65] op_sel_hi:[1,0,0] neg_lo:[1,0,0] neg_hi:[1,0,0]
	v_mfma_f32_16x16x32_bf16 v[58:61], v[152:155], v[188:191], v[58:61]
	v_mul_f32_e64 v10, v10, v8
	v_mul_f32_e64 v11, v11, v9
	v_pk_add_f32 v[6:7], v[6:7], 1.0 op_sel_hi:[1,0]
	v_exp_f32_e32 v10, v10
	v_exp_f32_e32 v11, v11
	v_rcp_f32_e32 v6, v6
	v_rcp_f32_e32 v7, v7
	v_cvt_pk_bf16_f32 v3, v3, v18
	v_pk_add_f32 v[10:11], v[10:11], 1.0 op_sel_hi:[1,0]
	flat_store_dwordx2 v[0:1], v[2:3] offset:64
	v_rcp_f32_e32 v10, v10
	v_rcp_f32_e32 v11, v11
	v_pk_mul_f32 v[2:3], v[6:7], v[4:5]
	v_add_f32_e32 v6, v58, v43
	v_mul_f32_e32 v2, v2, v6
	v_add_f32_e32 v6, v59, v43
	v_mul_f32_e32 v3, v3, v6
	v_pk_mul_f32 v[4:5], v[10:11], v[8:9]
	v_cvt_pk_bf16_f32 v2, v2, v3
	v_add_f32_e32 v3, v60, v43
	v_mul_f32_e32 v3, v4, v3
	v_add_f32_e32 v4, v61, v43
	v_mul_f32_e32 v4, v5, v4
	v_cvt_pk_bf16_f32 v3, v3, v4
	flat_store_dwordx2 v[0:1], v[2:3] offset:96
	s_cbranch_scc0 .LBB0_354
.LBB0_350:
	s_ashr_i32 s4, s60, 9
	s_ashr_i32 s5, s4, 31
	s_lshl_b64 s[50:51], s[4:5], 13
	s_and_b32 s4, s59, 0x1f80
	s_or_b32 s50, s50, s4
	s_nop 0
	s_barrier
	s_and_saveexec_b64 s[52:53], s[6:7]
	s_cbranch_execz .LBB0_352
	v_mov_b32_e32 v1, s51
	v_or_b32_e32 v0, s50, v196
	v_lshlrev_b64 v[0:1], 6, v[0:1]
	v_lshl_add_u64 v[224:225], s[48:49], 0, v[0:1]
	global_load_dwordx4 v[208:211], v[224:225], off
	global_load_dwordx4 v[212:215], v[224:225], off offset:16
	global_load_dwordx4 v[216:219], v[224:225], off offset:32
	s_nop 0
	global_load_dwordx4 v[220:223], v[224:225], off offset:48
